# odd in-projection epilogue: rs loads hoisted, counted waits (stores stay in flight)
# speedup vs baseline: 1.0078x; 1.0078x over previous
.LBB0_553:
	s_min_i32 s11, s43, 64
	s_lshr_b32 s11, s11, 4
	s_mul_i32 s18, s11, 0x1600
	s_ashr_i32 s19, s18, 31
	s_lshl_b64 s[18:19], s[18:19], 2
	v_lshl_add_u32 v164, s43, 8, v1
	s_add_u32 s11, s34, s18
	v_ashrrev_i32_e32 v165, 31, v164
	s_addc_u32 s13, s35, s19
	s_lshl_b32 s18, s42, 8
	v_lshl_add_u64 v[130:131], v[164:165], 2, s[6:7]
	s_ashr_i32 s19, s18, 31
	global_load_dword v174, v[130:131], off
	s_lshl_b64 s[18:19], s[18:19], 2
	s_add_u32 s11, s11, s18
	s_addc_u32 s13, s13, s19
	s_lshl_b32 s18, s38, 2
	s_add_u32 s18, s11, s18
	s_addc_u32 s19, s13, 0
	v_lshlrev_b32_e32 v130, 2, v156
	global_load_dwordx4 v[142:145], v130, s[18:19]
	global_load_dwordx4 v[138:141], v130, s[18:19] offset:16
	global_load_dwordx4 v[134:137], v130, s[18:19] offset:512
	s_nop 0
	global_load_dwordx4 v[130:133], v130, s[18:19] offset:528
	v_or_b32_e32 v184, 16, v164
	v_ashrrev_i32_e32 v185, 31, v184
	v_lshl_add_u64 v[184:185], v[184:185], 2, s[6:7]
	global_load_dword v198, v[184:185], off
	v_or_b32_e32 v186, 32, v164
	v_ashrrev_i32_e32 v187, 31, v186
	v_lshl_add_u64 v[186:187], v[186:187], 2, s[6:7]
	global_load_dword v199, v[186:187], off
	v_or_b32_e32 v188, 48, v164
	v_ashrrev_i32_e32 v189, 31, v188
	v_lshl_add_u64 v[188:189], v[188:189], 2, s[6:7]
	global_load_dword v200, v[188:189], off
	v_add_u32_e32 v190, 0x80, v164
	v_ashrrev_i32_e32 v191, 31, v190
	v_lshl_add_u64 v[190:191], v[190:191], 2, s[6:7]
	global_load_dword v201, v[190:191], off
	v_add_u32_e32 v192, 0x90, v164
	v_ashrrev_i32_e32 v193, 31, v192
	v_lshl_add_u64 v[192:193], v[192:193], 2, s[6:7]
	global_load_dword v202, v[192:193], off
	v_add_u32_e32 v194, 0xa0, v164
	v_ashrrev_i32_e32 v195, 31, v194
	v_lshl_add_u64 v[194:195], v[194:195], 2, s[6:7]
	global_load_dword v203, v[194:195], off
	v_add_u32_e32 v196, 0xb0, v164
	v_ashrrev_i32_e32 v197, 31, v196
	v_lshl_add_u64 v[196:197], v[196:197], 2, s[6:7]
	global_load_dword v204, v[196:197], off
	s_ashr_i32 s11, s42, 2
	s_cmp_eq_u32 s11, 1
	s_mul_hi_i32 s13, s11, 0x2200000
	s_mul_i32 s11, s11, 0x2200000
	s_cselect_b64 vcc, -1, 0
	s_add_u32 s11, s36, s11
	v_lshlrev_b64 v[170:171], 11, v[164:165]
	s_addc_u32 s13, s37, s13
	s_lshl_b32 s18, s42, 9
	s_and_b32 s18, s18, 0x600
	s_add_u32 s11, s11, s18
	s_addc_u32 s13, s13, 0
	s_lshl_b32 s18, s38, 1
	v_mov_b32_e32 v162, 0x3d800000
	s_add_u32 s18, s11, s18
	v_lshlrev_b32_e32 v166, 1, v156
	v_mov_b32_e32 v167, v0
	v_cndmask_b32_e32 v162, 1.0, v162, vcc
	s_addc_u32 s19, s13, 0
	v_or_b32_e32 v168, 16, v164
	v_lshl_add_u64 v[166:167], s[18:19], 0, v[166:167]
	v_ashrrev_i32_e32 v169, 31, v168
	v_lshl_add_u64 v[170:171], v[166:167], 0, v[170:171]
	v_lshl_add_u64 v[172:173], v[168:169], 2, s[6:7]
	v_readlane_b32 s50, v254, 10
	s_andn2_b64 vcc, exec, s[0:1]
	s_mov_b64 s[0:1], -1
	v_readlane_b32 s51, v254, 11
	s_waitcnt vmcnt(7)
	v_fmamk_f32 v165, v174, 0x3a800000, v225
	v_rsq_f32_e32 v174, v165
	s_nop 0
	v_pk_fma_f32 v[126:127], v[126:127], v[174:175], v[142:143] op_sel_hi:[1,0,1]
	v_pk_fma_f32 v[128:129], v[128:129], v[174:175], v[144:145] op_sel_hi:[1,0,1]
	v_pk_fma_f32 v[122:123], v[122:123], v[174:175], v[138:139] op_sel_hi:[1,0,1]
	v_pk_fma_f32 v[124:125], v[124:125], v[174:175], v[140:141] op_sel_hi:[1,0,1]
	v_pk_fma_f32 v[118:119], v[118:119], v[174:175], v[134:135] op_sel_hi:[1,0,1]
	v_pk_fma_f32 v[120:121], v[120:121], v[174:175], v[136:137] op_sel_hi:[1,0,1]
	v_pk_fma_f32 v[114:115], v[114:115], v[174:175], v[130:131] op_sel_hi:[1,0,1]
	v_pk_fma_f32 v[116:117], v[116:117], v[174:175], v[132:133] op_sel_hi:[1,0,1]
	v_pk_mul_f32 v[128:129], v[162:163], v[128:129] op_sel_hi:[0,1]
	v_pk_mul_f32 v[126:127], v[162:163], v[126:127] op_sel_hi:[0,1]
	v_pk_mul_f32 v[124:125], v[162:163], v[124:125] op_sel_hi:[0,1]
	v_pk_mul_f32 v[122:123], v[162:163], v[122:123] op_sel_hi:[0,1]
	v_pk_mul_f32 v[120:121], v[162:163], v[120:121] op_sel_hi:[0,1]
	v_pk_mul_f32 v[118:119], v[162:163], v[118:119] op_sel_hi:[0,1]
	v_pk_mul_f32 v[174:175], v[162:163], v[116:117] op_sel_hi:[0,1]
	v_pk_mul_f32 v[176:177], v[162:163], v[114:115] op_sel_hi:[0,1]
	v_cvt_pk_bf16_f32 v114, v126, v127
	v_cvt_pk_bf16_f32 v115, v128, v129
	v_cvt_pk_bf16_f32 v116, v122, v123
	v_cvt_pk_bf16_f32 v117, v124, v125
	v_cvt_pk_bf16_f32 v118, v118, v119
	v_cvt_pk_bf16_f32 v119, v120, v121
	v_cvt_pk_bf16_f32 v120, v176, v177
	v_cvt_pk_bf16_f32 v121, v174, v175
	global_store_dwordx4 v[170:171], v[114:117], off
	global_store_dwordx4 v[170:171], v[118:121], off offset:256
	s_nop 0
	v_or_b32_e32 v114, 32, v164
	v_lshlrev_b64 v[118:119], 11, v[168:169]
	v_ashrrev_i32_e32 v115, 31, v114
	v_lshl_add_u64 v[118:119], v[166:167], 0, v[118:119]
	v_lshl_add_u64 v[120:121], v[114:115], 2, s[6:7]
	s_waitcnt vmcnt(8)
	v_fmamk_f32 v116, v198, 0x3a800000, v225
	v_rsq_f32_e32 v116, v116
	s_nop 0
	v_pk_fma_f32 v[110:111], v[110:111], v[116:117], v[142:143] op_sel_hi:[1,0,1]
	v_pk_fma_f32 v[112:113], v[112:113], v[116:117], v[144:145] op_sel_hi:[1,0,1]
	v_pk_fma_f32 v[106:107], v[106:107], v[116:117], v[138:139] op_sel_hi:[1,0,1]
	v_pk_fma_f32 v[108:109], v[108:109], v[116:117], v[140:141] op_sel_hi:[1,0,1]
	v_pk_fma_f32 v[102:103], v[102:103], v[116:117], v[134:135] op_sel_hi:[1,0,1]
	v_pk_fma_f32 v[104:105], v[104:105], v[116:117], v[136:137] op_sel_hi:[1,0,1]
	v_pk_fma_f32 v[98:99], v[98:99], v[116:117], v[130:131] op_sel_hi:[1,0,1]
	v_pk_fma_f32 v[100:101], v[100:101], v[116:117], v[132:133] op_sel_hi:[1,0,1]
	v_pk_mul_f32 v[112:113], v[162:163], v[112:113] op_sel_hi:[0,1]
	v_pk_mul_f32 v[110:111], v[162:163], v[110:111] op_sel_hi:[0,1]
	v_pk_mul_f32 v[108:109], v[162:163], v[108:109] op_sel_hi:[0,1]
	v_pk_mul_f32 v[106:107], v[162:163], v[106:107] op_sel_hi:[0,1]
	v_pk_mul_f32 v[104:105], v[162:163], v[104:105] op_sel_hi:[0,1]
	v_pk_mul_f32 v[102:103], v[162:163], v[102:103] op_sel_hi:[0,1]
	v_pk_mul_f32 v[116:117], v[162:163], v[100:101] op_sel_hi:[0,1]
	v_pk_mul_f32 v[122:123], v[162:163], v[98:99] op_sel_hi:[0,1]
	v_cvt_pk_bf16_f32 v98, v110, v111
	v_cvt_pk_bf16_f32 v99, v112, v113
	v_cvt_pk_bf16_f32 v100, v106, v107
	v_cvt_pk_bf16_f32 v101, v108, v109
	v_cvt_pk_bf16_f32 v102, v102, v103
	v_cvt_pk_bf16_f32 v103, v104, v105
	v_cvt_pk_bf16_f32 v104, v122, v123
	v_cvt_pk_bf16_f32 v105, v116, v117
	global_store_dwordx4 v[118:119], v[98:101], off
	global_store_dwordx4 v[118:119], v[102:105], off offset:256
	s_nop 0
	v_or_b32_e32 v98, 48, v164
	v_lshlrev_b64 v[102:103], 11, v[114:115]
	v_ashrrev_i32_e32 v99, 31, v98
	v_lshl_add_u64 v[102:103], v[166:167], 0, v[102:103]
	v_lshl_add_u64 v[104:105], v[98:99], 2, s[6:7]
	s_waitcnt vmcnt(9)
	v_fmamk_f32 v100, v199, 0x3a800000, v225
	v_rsq_f32_e32 v100, v100
	s_nop 0
	v_pk_fma_f32 v[94:95], v[94:95], v[100:101], v[142:143] op_sel_hi:[1,0,1]
	v_pk_fma_f32 v[96:97], v[96:97], v[100:101], v[144:145] op_sel_hi:[1,0,1]
	v_pk_fma_f32 v[90:91], v[90:91], v[100:101], v[138:139] op_sel_hi:[1,0,1]
	v_pk_fma_f32 v[92:93], v[92:93], v[100:101], v[140:141] op_sel_hi:[1,0,1]
	v_pk_fma_f32 v[86:87], v[86:87], v[100:101], v[134:135] op_sel_hi:[1,0,1]
	v_pk_fma_f32 v[88:89], v[88:89], v[100:101], v[136:137] op_sel_hi:[1,0,1]
	v_pk_fma_f32 v[82:83], v[82:83], v[100:101], v[130:131] op_sel_hi:[1,0,1]
	v_pk_fma_f32 v[84:85], v[84:85], v[100:101], v[132:133] op_sel_hi:[1,0,1]
	v_pk_mul_f32 v[96:97], v[162:163], v[96:97] op_sel_hi:[0,1]
	v_pk_mul_f32 v[94:95], v[162:163], v[94:95] op_sel_hi:[0,1]
	v_pk_mul_f32 v[92:93], v[162:163], v[92:93] op_sel_hi:[0,1]
	v_pk_mul_f32 v[90:91], v[162:163], v[90:91] op_sel_hi:[0,1]
	v_pk_mul_f32 v[88:89], v[162:163], v[88:89] op_sel_hi:[0,1]
	v_pk_mul_f32 v[86:87], v[162:163], v[86:87] op_sel_hi:[0,1]
	v_pk_mul_f32 v[100:101], v[162:163], v[84:85] op_sel_hi:[0,1]
	v_pk_mul_f32 v[106:107], v[162:163], v[82:83] op_sel_hi:[0,1]
	v_cvt_pk_bf16_f32 v82, v94, v95
	v_cvt_pk_bf16_f32 v83, v96, v97
	v_cvt_pk_bf16_f32 v84, v90, v91
	v_cvt_pk_bf16_f32 v85, v92, v93
	v_cvt_pk_bf16_f32 v86, v86, v87
	v_cvt_pk_bf16_f32 v87, v88, v89
	v_cvt_pk_bf16_f32 v88, v106, v107
	v_cvt_pk_bf16_f32 v89, v100, v101
	global_store_dwordx4 v[102:103], v[82:85], off
	global_store_dwordx4 v[102:103], v[86:89], off offset:256
	s_nop 0
	v_add_u32_e32 v82, 0x80, v164
	v_lshlrev_b64 v[86:87], 11, v[98:99]
	v_ashrrev_i32_e32 v83, 31, v82
	v_lshl_add_u64 v[86:87], v[166:167], 0, v[86:87]
	v_lshl_add_u64 v[88:89], v[82:83], 2, s[6:7]
	s_waitcnt vmcnt(10)
	v_fmamk_f32 v84, v200, 0x3a800000, v225
	v_rsq_f32_e32 v84, v84
	s_nop 0
	v_pk_fma_f32 v[78:79], v[78:79], v[84:85], v[142:143] op_sel_hi:[1,0,1]
	v_pk_fma_f32 v[80:81], v[80:81], v[84:85], v[144:145] op_sel_hi:[1,0,1]
	v_pk_fma_f32 v[74:75], v[74:75], v[84:85], v[138:139] op_sel_hi:[1,0,1]
	v_pk_fma_f32 v[76:77], v[76:77], v[84:85], v[140:141] op_sel_hi:[1,0,1]
	v_pk_fma_f32 v[70:71], v[70:71], v[84:85], v[134:135] op_sel_hi:[1,0,1]
	v_pk_fma_f32 v[72:73], v[72:73], v[84:85], v[136:137] op_sel_hi:[1,0,1]
	v_pk_fma_f32 v[66:67], v[66:67], v[84:85], v[130:131] op_sel_hi:[1,0,1]
	v_pk_fma_f32 v[68:69], v[68:69], v[84:85], v[132:133] op_sel_hi:[1,0,1]
	v_pk_mul_f32 v[80:81], v[162:163], v[80:81] op_sel_hi:[0,1]
	v_pk_mul_f32 v[78:79], v[162:163], v[78:79] op_sel_hi:[0,1]
	v_pk_mul_f32 v[76:77], v[162:163], v[76:77] op_sel_hi:[0,1]
	v_pk_mul_f32 v[74:75], v[162:163], v[74:75] op_sel_hi:[0,1]
	v_pk_mul_f32 v[72:73], v[162:163], v[72:73] op_sel_hi:[0,1]
	v_pk_mul_f32 v[70:71], v[162:163], v[70:71] op_sel_hi:[0,1]
	v_pk_mul_f32 v[84:85], v[162:163], v[68:69] op_sel_hi:[0,1]
	v_pk_mul_f32 v[90:91], v[162:163], v[66:67] op_sel_hi:[0,1]
	v_cvt_pk_bf16_f32 v66, v78, v79
	v_cvt_pk_bf16_f32 v67, v80, v81
	v_cvt_pk_bf16_f32 v68, v74, v75
	v_cvt_pk_bf16_f32 v69, v76, v77
	v_cvt_pk_bf16_f32 v70, v70, v71
	v_cvt_pk_bf16_f32 v71, v72, v73
	v_cvt_pk_bf16_f32 v72, v90, v91
	v_cvt_pk_bf16_f32 v73, v84, v85
	global_store_dwordx4 v[86:87], v[66:69], off
	global_store_dwordx4 v[86:87], v[70:73], off offset:256
	s_nop 0
	v_add_u32_e32 v66, 0x90, v164
	v_lshlrev_b64 v[70:71], 11, v[82:83]
	v_ashrrev_i32_e32 v67, 31, v66
	v_lshl_add_u64 v[70:71], v[166:167], 0, v[70:71]
	v_lshl_add_u64 v[72:73], v[66:67], 2, s[6:7]
	s_waitcnt vmcnt(11)
	v_fmamk_f32 v68, v201, 0x3a800000, v225
	v_rsq_f32_e32 v68, v68
	s_nop 0
	v_pk_fma_f32 v[62:63], v[62:63], v[68:69], v[142:143] op_sel_hi:[1,0,1]
	v_pk_fma_f32 v[64:65], v[64:65], v[68:69], v[144:145] op_sel_hi:[1,0,1]
	v_pk_fma_f32 v[58:59], v[58:59], v[68:69], v[138:139] op_sel_hi:[1,0,1]
	v_pk_fma_f32 v[60:61], v[60:61], v[68:69], v[140:141] op_sel_hi:[1,0,1]
	v_pk_fma_f32 v[54:55], v[54:55], v[68:69], v[134:135] op_sel_hi:[1,0,1]
	v_pk_fma_f32 v[56:57], v[56:57], v[68:69], v[136:137] op_sel_hi:[1,0,1]
	v_pk_fma_f32 v[50:51], v[50:51], v[68:69], v[130:131] op_sel_hi:[1,0,1]
	v_pk_fma_f32 v[52:53], v[52:53], v[68:69], v[132:133] op_sel_hi:[1,0,1]
	v_pk_mul_f32 v[64:65], v[162:163], v[64:65] op_sel_hi:[0,1]
	v_pk_mul_f32 v[62:63], v[162:163], v[62:63] op_sel_hi:[0,1]
	v_pk_mul_f32 v[60:61], v[162:163], v[60:61] op_sel_hi:[0,1]
	v_pk_mul_f32 v[58:59], v[162:163], v[58:59] op_sel_hi:[0,1]
	v_pk_mul_f32 v[56:57], v[162:163], v[56:57] op_sel_hi:[0,1]
	v_pk_mul_f32 v[54:55], v[162:163], v[54:55] op_sel_hi:[0,1]
	v_pk_mul_f32 v[68:69], v[162:163], v[52:53] op_sel_hi:[0,1]
	v_pk_mul_f32 v[74:75], v[162:163], v[50:51] op_sel_hi:[0,1]
	v_cvt_pk_bf16_f32 v50, v62, v63
	v_cvt_pk_bf16_f32 v51, v64, v65
	v_cvt_pk_bf16_f32 v52, v58, v59
	v_cvt_pk_bf16_f32 v53, v60, v61
	v_cvt_pk_bf16_f32 v54, v54, v55
	v_cvt_pk_bf16_f32 v55, v56, v57
	v_cvt_pk_bf16_f32 v56, v74, v75
	v_cvt_pk_bf16_f32 v57, v68, v69
	global_store_dwordx4 v[70:71], v[50:53], off
	global_store_dwordx4 v[70:71], v[54:57], off offset:256
	s_nop 0
	v_add_u32_e32 v50, 0xa0, v164
	v_lshlrev_b64 v[54:55], 11, v[66:67]
	v_ashrrev_i32_e32 v51, 31, v50
	v_lshl_add_u64 v[54:55], v[166:167], 0, v[54:55]
	v_lshl_add_u64 v[56:57], v[50:51], 2, s[6:7]
	s_waitcnt vmcnt(12)
	v_fmamk_f32 v52, v202, 0x3a800000, v225
	v_rsq_f32_e32 v52, v52
	s_nop 0
	v_pk_fma_f32 v[46:47], v[46:47], v[52:53], v[142:143] op_sel_hi:[1,0,1]
	v_pk_fma_f32 v[48:49], v[48:49], v[52:53], v[144:145] op_sel_hi:[1,0,1]
	v_pk_fma_f32 v[42:43], v[42:43], v[52:53], v[138:139] op_sel_hi:[1,0,1]
	v_pk_fma_f32 v[44:45], v[44:45], v[52:53], v[140:141] op_sel_hi:[1,0,1]
	v_pk_fma_f32 v[38:39], v[38:39], v[52:53], v[134:135] op_sel_hi:[1,0,1]
	v_pk_fma_f32 v[40:41], v[40:41], v[52:53], v[136:137] op_sel_hi:[1,0,1]
	v_pk_fma_f32 v[34:35], v[34:35], v[52:53], v[130:131] op_sel_hi:[1,0,1]
	v_pk_fma_f32 v[36:37], v[36:37], v[52:53], v[132:133] op_sel_hi:[1,0,1]
	v_pk_mul_f32 v[48:49], v[162:163], v[48:49] op_sel_hi:[0,1]
	v_pk_mul_f32 v[46:47], v[162:163], v[46:47] op_sel_hi:[0,1]
	v_pk_mul_f32 v[44:45], v[162:163], v[44:45] op_sel_hi:[0,1]
	v_pk_mul_f32 v[42:43], v[162:163], v[42:43] op_sel_hi:[0,1]
	v_pk_mul_f32 v[40:41], v[162:163], v[40:41] op_sel_hi:[0,1]
	v_pk_mul_f32 v[38:39], v[162:163], v[38:39] op_sel_hi:[0,1]
	v_pk_mul_f32 v[52:53], v[162:163], v[36:37] op_sel_hi:[0,1]
	v_pk_mul_f32 v[58:59], v[162:163], v[34:35] op_sel_hi:[0,1]
	v_cvt_pk_bf16_f32 v34, v46, v47
	v_cvt_pk_bf16_f32 v35, v48, v49
	v_cvt_pk_bf16_f32 v36, v42, v43
	v_cvt_pk_bf16_f32 v37, v44, v45
	v_cvt_pk_bf16_f32 v38, v38, v39
	v_cvt_pk_bf16_f32 v39, v40, v41
	v_cvt_pk_bf16_f32 v40, v58, v59
	v_cvt_pk_bf16_f32 v41, v52, v53
	global_store_dwordx4 v[54:55], v[34:37], off
	global_store_dwordx4 v[54:55], v[38:41], off offset:256
	s_nop 0
	v_add_u32_e32 v34, 0xb0, v164
	v_lshlrev_b64 v[38:39], 11, v[50:51]
	v_ashrrev_i32_e32 v35, 31, v34
	v_lshl_add_u64 v[38:39], v[166:167], 0, v[38:39]
	v_lshl_add_u64 v[40:41], v[34:35], 2, s[6:7]
	s_waitcnt vmcnt(13)
	v_fmamk_f32 v36, v203, 0x3a800000, v225
	v_rsq_f32_e32 v36, v36
	s_nop 0
	v_pk_fma_f32 v[30:31], v[30:31], v[36:37], v[142:143] op_sel_hi:[1,0,1]
	v_pk_fma_f32 v[32:33], v[32:33], v[36:37], v[144:145] op_sel_hi:[1,0,1]
	v_pk_fma_f32 v[26:27], v[26:27], v[36:37], v[138:139] op_sel_hi:[1,0,1]
	v_pk_fma_f32 v[28:29], v[28:29], v[36:37], v[140:141] op_sel_hi:[1,0,1]
	v_pk_fma_f32 v[22:23], v[22:23], v[36:37], v[134:135] op_sel_hi:[1,0,1]
	v_pk_fma_f32 v[24:25], v[24:25], v[36:37], v[136:137] op_sel_hi:[1,0,1]
	v_pk_fma_f32 v[18:19], v[18:19], v[36:37], v[130:131] op_sel_hi:[1,0,1]
	v_pk_fma_f32 v[20:21], v[20:21], v[36:37], v[132:133] op_sel_hi:[1,0,1]
	v_pk_mul_f32 v[32:33], v[162:163], v[32:33] op_sel_hi:[0,1]
	v_pk_mul_f32 v[30:31], v[162:163], v[30:31] op_sel_hi:[0,1]
	v_pk_mul_f32 v[28:29], v[162:163], v[28:29] op_sel_hi:[0,1]
	v_pk_mul_f32 v[26:27], v[162:163], v[26:27] op_sel_hi:[0,1]
	v_pk_mul_f32 v[24:25], v[162:163], v[24:25] op_sel_hi:[0,1]
	v_pk_mul_f32 v[22:23], v[162:163], v[22:23] op_sel_hi:[0,1]
	v_pk_mul_f32 v[36:37], v[162:163], v[20:21] op_sel_hi:[0,1]
	v_pk_mul_f32 v[42:43], v[162:163], v[18:19] op_sel_hi:[0,1]
	v_cvt_pk_bf16_f32 v18, v30, v31
	v_cvt_pk_bf16_f32 v19, v32, v33
	v_cvt_pk_bf16_f32 v20, v26, v27
	v_cvt_pk_bf16_f32 v21, v28, v29
	v_cvt_pk_bf16_f32 v22, v22, v23
	v_cvt_pk_bf16_f32 v23, v24, v25
	v_cvt_pk_bf16_f32 v24, v42, v43
	v_cvt_pk_bf16_f32 v25, v36, v37
	global_store_dwordx4 v[38:39], v[18:21], off
	global_store_dwordx4 v[38:39], v[22:25], off offset:256
	s_nop 0
	v_lshlrev_b64 v[20:21], 11, v[34:35]
	v_lshl_add_u64 v[20:21], v[166:167], 0, v[20:21]
	s_waitcnt vmcnt(14)
	v_fmamk_f32 v18, v204, 0x3a800000, v225
	v_rsq_f32_e32 v18, v18
	s_nop 0
	v_pk_fma_f32 v[14:15], v[14:15], v[18:19], v[142:143] op_sel_hi:[1,0,1]
	v_pk_fma_f32 v[16:17], v[16:17], v[18:19], v[144:145] op_sel_hi:[1,0,1]
	v_pk_fma_f32 v[10:11], v[10:11], v[18:19], v[138:139] op_sel_hi:[1,0,1]
	v_pk_fma_f32 v[12:13], v[12:13], v[18:19], v[140:141] op_sel_hi:[1,0,1]
	v_pk_fma_f32 v[6:7], v[6:7], v[18:19], v[134:135] op_sel_hi:[1,0,1]
	v_pk_fma_f32 v[8:9], v[8:9], v[18:19], v[136:137] op_sel_hi:[1,0,1]
	v_pk_fma_f32 v[2:3], v[2:3], v[18:19], v[130:131] op_sel_hi:[1,0,1]
	v_pk_fma_f32 v[4:5], v[4:5], v[18:19], v[132:133] op_sel_hi:[1,0,1]
	v_pk_mul_f32 v[16:17], v[162:163], v[16:17] op_sel_hi:[0,1]
	v_pk_mul_f32 v[14:15], v[162:163], v[14:15] op_sel_hi:[0,1]
	v_pk_mul_f32 v[12:13], v[162:163], v[12:13] op_sel_hi:[0,1]
	v_pk_mul_f32 v[10:11], v[162:163], v[10:11] op_sel_hi:[0,1]
	v_pk_mul_f32 v[8:9], v[162:163], v[8:9] op_sel_hi:[0,1]
	v_pk_mul_f32 v[6:7], v[162:163], v[6:7] op_sel_hi:[0,1]
	v_pk_mul_f32 v[18:19], v[162:163], v[4:5] op_sel_hi:[0,1]
	v_pk_mul_f32 v[22:23], v[162:163], v[2:3] op_sel_hi:[0,1]
	v_cvt_pk_bf16_f32 v2, v14, v15
	v_cvt_pk_bf16_f32 v3, v16, v17
	v_cvt_pk_bf16_f32 v4, v10, v11
	v_cvt_pk_bf16_f32 v5, v12, v13
	v_cvt_pk_bf16_f32 v6, v6, v7
	v_cvt_pk_bf16_f32 v7, v8, v9
	v_cvt_pk_bf16_f32 v8, v22, v23
	v_cvt_pk_bf16_f32 v9, v18, v19
	global_store_dwordx4 v[20:21], v[2:5], off
	global_store_dwordx4 v[20:21], v[6:9], off offset:256
	s_cbranch_vccnz .LBB0_543
	s_andn2_b64 vcc, exec, s[4:5]
	s_cbranch_vccnz .LBB0_542
	s_barrier
	s_branch .LBB0_542
